# skip MFMA blocks whose 64-row quarter is outside the valid rows of cross-attention sample units (cascore/caout)
# speedup vs baseline: 1.0033x; 1.0002x over previous
; #define PG8_BAR __builtin_amdgcn_s_barrier()
; template <class Epi, class Sched>
; __device__ __forceinline__ void gemm_phase(LAS unsigned char* lds, const GemmP g, const Sched& S, const Epi& E, int tid) {
;     ...
; #pragma unroll
;         for (int a = 0; a < 2; ++a)
; #pragma unroll
;             for (int b = 0; b < 2; ++b)
; #pragma unroll
;                 for (int m = 0; m < 4; ++m)
; #pragma unroll
;                     for (int n = 0; n < 2; ++n) acc[a][b][m][n] = (f32x4){0.f, 0.f, 0.f, 0.f};
;         cur = nxt; cA = nA; cB = nB; ++ui;
;         if (wr == 1) PG8_BAR;
;     __device__ __forceinline__ bool next(int i, Unit& u) const {
;         const int L = i * G + c; if (L >= 1024 + 128) return false;
;         int row0, bb, hp;
;         if (L < 1024) { const int pm = L >> 2; hp = L & 3; row0 = pm * BM; bb = pm >> 4; u.vlo = 0; u.vhi = 0x7fffffff; }
;         else { const int s = L - 1024, b = s >> 2; hp = s & 3; const int r = MP + DSEQ * b; row0 = r < M - BM ? r : M - BM; bb = NB + b; u.vlo = r; u.vhi = r + DSEQ; }
.LBB0_995:
	s_add_u32 s5, s28, 0x100
	s_addc_u32 s56, s29, 0
	s_add_u32 s26, s26, 0x40080
	v_mov_b32_e32 v0, 0
	s_addc_u32 s27, s27, 0
	s_mov_b32 s57, -2
	v_mov_b32_e32 v1, v0
	v_mov_b32_e32 v2, v0
	v_mov_b32_e32 v3, v0
	v_mov_b32_e32 v4, v0
	v_mov_b32_e32 v5, v0
	v_mov_b32_e32 v6, v0
	v_mov_b32_e32 v7, v0
	v_mov_b32_e32 v16, v0
	v_mov_b32_e32 v17, v0
	v_mov_b32_e32 v18, v0
	v_mov_b32_e32 v19, v0
	v_mov_b32_e32 v20, v0
	v_mov_b32_e32 v21, v0
	v_mov_b32_e32 v22, v0
	v_mov_b32_e32 v23, v0
	v_mov_b32_e32 v32, v0
	v_mov_b32_e32 v33, v0
	v_mov_b32_e32 v34, v0
	v_mov_b32_e32 v35, v0
	v_mov_b32_e32 v36, v0
	v_mov_b32_e32 v37, v0
	v_mov_b32_e32 v38, v0
	v_mov_b32_e32 v39, v0
	v_mov_b32_e32 v48, v0
	v_mov_b32_e32 v49, v0
	v_mov_b32_e32 v50, v0
	v_mov_b32_e32 v51, v0
	v_mov_b32_e32 v52, v0
	v_mov_b32_e32 v53, v0
	v_mov_b32_e32 v54, v0
	v_mov_b32_e32 v55, v0
	v_mov_b32_e32 v8, v0
	v_mov_b32_e32 v9, v0
	v_mov_b32_e32 v10, v0
	v_mov_b32_e32 v11, v0
	v_mov_b32_e32 v12, v0
	v_mov_b32_e32 v13, v0
	v_mov_b32_e32 v14, v0
	v_mov_b32_e32 v15, v0
	v_mov_b32_e32 v24, v0
	v_mov_b32_e32 v25, v0
	v_mov_b32_e32 v26, v0
	v_mov_b32_e32 v27, v0
	v_mov_b32_e32 v28, v0
	v_mov_b32_e32 v29, v0
	v_mov_b32_e32 v30, v0
	v_mov_b32_e32 v31, v0
	v_mov_b32_e32 v40, v0
	v_mov_b32_e32 v41, v0
	v_mov_b32_e32 v42, v0
	v_mov_b32_e32 v43, v0
	v_mov_b32_e32 v44, v0
	v_mov_b32_e32 v45, v0
	v_mov_b32_e32 v46, v0
	v_mov_b32_e32 v47, v0
	v_mov_b32_e32 v56, v0
	v_mov_b32_e32 v57, v0
	v_mov_b32_e32 v58, v0
	v_mov_b32_e32 v59, v0
	v_mov_b32_e32 v60, v0
	v_mov_b32_e32 v61, v0
	v_mov_b32_e32 v62, v0
	v_mov_b32_e32 v63, v0
	v_mov_b32_e32 v64, v0
	v_mov_b32_e32 v65, v0
	v_mov_b32_e32 v66, v0
	v_mov_b32_e32 v67, v0
	v_mov_b32_e32 v68, v0
	v_mov_b32_e32 v69, v0
	v_mov_b32_e32 v70, v0
	v_mov_b32_e32 v71, v0
	v_mov_b32_e32 v80, v0
	v_mov_b32_e32 v81, v0
	v_mov_b32_e32 v82, v0
	v_mov_b32_e32 v83, v0
	v_mov_b32_e32 v84, v0
	v_mov_b32_e32 v85, v0
	v_mov_b32_e32 v86, v0
	v_mov_b32_e32 v87, v0
	v_mov_b32_e32 v96, v0
	v_mov_b32_e32 v97, v0
	v_mov_b32_e32 v98, v0
	v_mov_b32_e32 v99, v0
	v_mov_b32_e32 v100, v0
	v_mov_b32_e32 v101, v0
	v_mov_b32_e32 v102, v0
	v_mov_b32_e32 v103, v0
	v_mov_b32_e32 v112, v0
	v_mov_b32_e32 v113, v0
	v_mov_b32_e32 v114, v0
	v_mov_b32_e32 v115, v0
	v_mov_b32_e32 v116, v0
	v_mov_b32_e32 v117, v0
	v_mov_b32_e32 v118, v0
	v_mov_b32_e32 v119, v0
	v_mov_b32_e32 v72, v0
	v_mov_b32_e32 v73, v0
	v_mov_b32_e32 v74, v0
	v_mov_b32_e32 v75, v0
	v_mov_b32_e32 v76, v0
	v_mov_b32_e32 v77, v0
	v_mov_b32_e32 v78, v0
	v_mov_b32_e32 v79, v0
	v_mov_b32_e32 v88, v0
	v_mov_b32_e32 v89, v0
	v_mov_b32_e32 v90, v0
	v_mov_b32_e32 v91, v0
	v_mov_b32_e32 v92, v0
	v_mov_b32_e32 v93, v0
	v_mov_b32_e32 v94, v0
	v_mov_b32_e32 v95, v0
	v_mov_b32_e32 v104, v0
	v_mov_b32_e32 v105, v0
	v_mov_b32_e32 v106, v0
	v_mov_b32_e32 v107, v0
	v_mov_b32_e32 v108, v0
	v_mov_b32_e32 v109, v0
	v_mov_b32_e32 v110, v0
	v_mov_b32_e32 v111, v0
	v_mov_b32_e32 v120, v0
	v_mov_b32_e32 v121, v0
	v_mov_b32_e32 v122, v0
	v_mov_b32_e32 v123, v0
	v_mov_b32_e32 v124, v0
	v_mov_b32_e32 v125, v0
	v_mov_b32_e32 v126, v0
	v_mov_b32_e32 v127, v0
	s_sub_i32 s32, s44, s4
	s_bfe_u32 s98, s32, 0x10006
	s_bfe_u32 s32, s32, 0x10007
	s_cmp_lg_u64 s[10:11], 0
	s_cselect_b32 s99, 1, 0
	s_xor_b32 s98, s98, s99
	s_or_b32 s99, s98, s32
	s_xor_b32 s32, s32, 1
	s_or_b32 s98, s98, s32
	s_cmp_eq_u32 s43, 0x7fffffff
	s_cselect_b32 s32, 0, s99
	s_cselect_b32 s98, 0, s98

; #define PG8_STAGE(bufoff, gbase, voff) do { _Pragma("unroll") for (int _i = 0; _i < 2; ++_i) \
;         __builtin_amdgcn_global_load_lds((const unsigned*)((const char*)(gbase) + (voff)[_i]), (LAS unsigned*)(lds + (bufoff) + ldsw + _i * 8192), 16, 0, 0); } while (0)
; #define PG8_LDA(dst, b, h) do { _Pragma("unroll") for (int m = 0; m < 4; ++m) _Pragma("unroll") for (int k = 0; k < 2; ++k) dst[m][k] = *(const LAS bf16x8*)(lds + PG8_SA(b, h) + aoff + m * 2048 + k * 1024); } while (0)
; #define PG8_MMA(ai, bj, At, Bt) do { __builtin_amdgcn_s_setprio(1); _Pragma("unroll") for (int m = 0; m < 4; ++m) _Pragma("unroll") for (int n = 0; n < 2; ++n) _Pragma("unroll") for (int k = 0; k < 2; ++k) \
;         acc[ai][bj][m][n] = __builtin_amdgcn_mfma_f32_16x16x32_bf16(Bt[n][k], At[m][k], acc[ai][bj][m][n], 0, 0, 0); __builtin_amdgcn_s_setprio(0); } while (0)
; #define PG8_WAIT_V(n) asm volatile("s_waitcnt vmcnt(" #n ")" ::: "memory")
; #define PG8_WAIT_L(n) asm volatile("s_waitcnt lgkmcnt(" #n ")" ::: "memory")
; #define PG8_BAR __builtin_amdgcn_s_barrier()
; #define PG8_SCHED __builtin_amdgcn_sched_barrier(0)
; template <class Epi, class Sched>
; __device__ __forceinline__ void gemm_phase(LAS unsigned char* lds, const GemmP g, const Sched& S, const Epi& E, int tid) {
;     ...
;             PG8_WAIT_V(8); PG8_WAIT_L(0); PG8_BAR; PG8_MMA(0, 0, At, B0); PG8_MMA(0, 1, At, B1); PG8_BAR; PG8_SCHED;
;             PG8_LDA(At, 0, 1); PG8_STAGE(PG8_SB(0, 0), b2, voffB); PG8_STAGE(PG8_SB(0, 1), b2 + hstepB, voffB); PG8_STAGE(PG8_SA(0, 0), a2, voffA);
;             PG8_WAIT_V(8); PG8_WAIT_L(0); PG8_BAR; PG8_MMA(1, 0, At, B0); PG8_MMA(1, 1, At, B1); PG8_BAR; PG8_SCHED;
.Lfirstit_3:
	s_waitcnt lgkmcnt(0)
	s_barrier
	s_cmp_lg_u32 s32, 0
	s_cbranch_scc1 .Lsk_cs_1
	s_setprio 1
	s_waitcnt lgkmcnt(0)
	v_mfma_f32_16x16x32_bf16 v[124:127], v[140:143], v[176:179], v[124:127]
	v_mfma_f32_16x16x32_bf16 v[120:123], v[148:151], v[176:179], v[120:123]
	v_mfma_f32_16x16x32_bf16 v[108:111], v[140:143], v[184:187], v[108:111]
	v_mfma_f32_16x16x32_bf16 v[104:107], v[148:151], v[184:187], v[104:107]
	v_mfma_f32_16x16x32_bf16 v[92:95], v[140:143], v[192:195], v[92:95]
	v_mfma_f32_16x16x32_bf16 v[88:91], v[148:151], v[192:195], v[88:91]
	v_mfma_f32_16x16x32_bf16 v[76:79], v[140:143], v[210:213], v[76:79]
	v_mfma_f32_16x16x32_bf16 v[72:75], v[148:151], v[210:213], v[72:75]
	v_mfma_f32_16x16x32_bf16 v[124:127], v[144:147], v[180:183], v[124:127]
	v_mfma_f32_16x16x32_bf16 v[120:123], v[152:155], v[180:183], v[120:123]
	v_mfma_f32_16x16x32_bf16 v[108:111], v[144:147], v[188:191], v[108:111]
	v_mfma_f32_16x16x32_bf16 v[104:107], v[152:155], v[188:191], v[104:107]
	v_mfma_f32_16x16x32_bf16 v[92:95], v[144:147], v[206:209], v[92:95]
	v_mfma_f32_16x16x32_bf16 v[88:91], v[152:155], v[206:209], v[88:91]
	v_mfma_f32_16x16x32_bf16 v[76:79], v[144:147], v[214:217], v[76:79]
	v_mfma_f32_16x16x32_bf16 v[72:75], v[152:155], v[214:217], v[72:75]
	s_setprio 0
	s_setprio 1
	v_mfma_f32_16x16x32_bf16 v[116:119], v[156:159], v[176:179], v[116:119]
	v_mfma_f32_16x16x32_bf16 v[112:115], v[168:171], v[176:179], v[112:115]
	v_mfma_f32_16x16x32_bf16 v[100:103], v[156:159], v[184:187], v[100:103]
	v_mfma_f32_16x16x32_bf16 v[96:99], v[168:171], v[184:187], v[96:99]
	v_mfma_f32_16x16x32_bf16 v[84:87], v[156:159], v[192:195], v[84:87]
	v_mfma_f32_16x16x32_bf16 v[80:83], v[168:171], v[192:195], v[80:83]
	v_mfma_f32_16x16x32_bf16 v[68:71], v[156:159], v[210:213], v[68:71]
	v_mfma_f32_16x16x32_bf16 v[64:67], v[168:171], v[210:213], v[64:67]
	v_mfma_f32_16x16x32_bf16 v[116:119], v[160:163], v[180:183], v[116:119]
	v_mfma_f32_16x16x32_bf16 v[112:115], v[172:175], v[180:183], v[112:115]
	v_mfma_f32_16x16x32_bf16 v[100:103], v[160:163], v[188:191], v[100:103]
	v_mfma_f32_16x16x32_bf16 v[96:99], v[172:175], v[188:191], v[96:99]
	v_mfma_f32_16x16x32_bf16 v[84:87], v[160:163], v[206:209], v[84:87]
	v_mfma_f32_16x16x32_bf16 v[80:83], v[172:175], v[206:209], v[80:83]
	v_mfma_f32_16x16x32_bf16 v[68:71], v[160:163], v[214:217], v[68:71]
	v_mfma_f32_16x16x32_bf16 v[64:67], v[172:175], v[214:217], v[64:67]
	s_setprio 0
.Lsk_cs_1:
	s_barrier
	s_add_i32 s60, s60, s41
	v_lshl_add_u64 v[164:165], s[28:29], 0, v[130:131]
	s_mov_b32 m0, s60
	ds_read_b128 v[176:179], v167 offset:16384
	ds_read_b128 v[180:183], v167 offset:17408
	ds_read_b128 v[184:187], v167 offset:18432
	ds_read_b128 v[188:191], v167 offset:19456
	ds_read_b128 v[192:195], v167 offset:20480
	ds_read_b128 v[206:209], v167 offset:21504
	ds_read_b128 v[210:213], v167 offset:22528
	ds_read_b128 v[214:217], v167 offset:23552
	global_load_lds_dwordx4 v[164:165], off
	s_add_i32 m0, s60, 0x2000
	s_add_u32 s60, s28, 0x40000
	v_lshl_add_u64 v[198:199], s[28:29], 0, v[134:135]
	s_addc_u32 s61, s29, 0
	s_add_i32 s62, s62, s41
	global_load_lds_dwordx4 v[198:199], off
	v_lshl_add_u64 v[200:201], s[60:61], 0, v[130:131]
	s_mov_b32 m0, s62
	v_lshl_add_u64 v[220:221], s[30:31], 0, v[132:133]
	global_load_lds_dwordx4 v[200:201], off
	v_lshl_add_u64 v[200:201], s[60:61], 0, v[134:135]
	s_add_i32 m0, s62, 0x2000
	s_nop 0
	global_load_lds_dwordx4 v[200:201], off
	v_lshl_add_u64 v[200:201], s[30:31], 0, v[128:129]
	s_mov_b32 m0, s42
	s_nop 0
	global_load_lds_dwordx4 v[200:201], off
	s_mov_b32 m0, s45
	s_nop 0
	global_load_lds_dwordx4 v[220:221], off
	s_waitcnt vmcnt(8)
	s_waitcnt lgkmcnt(0)
	s_barrier
	s_cmp_lg_u32 s98, 0
	s_cbranch_scc1 .Lsk_cs_2
	s_setprio 1
	s_waitcnt lgkmcnt(0)
	v_mfma_f32_16x16x32_bf16 v[60:63], v[140:143], v[176:179], v[60:63]
	v_mfma_f32_16x16x32_bf16 v[56:59], v[148:151], v[176:179], v[56:59]
	v_mfma_f32_16x16x32_bf16 v[44:47], v[140:143], v[184:187], v[44:47]
	v_mfma_f32_16x16x32_bf16 v[40:43], v[148:151], v[184:187], v[40:43]
	v_mfma_f32_16x16x32_bf16 v[28:31], v[140:143], v[192:195], v[28:31]
	v_mfma_f32_16x16x32_bf16 v[24:27], v[148:151], v[192:195], v[24:27]
	v_mfma_f32_16x16x32_bf16 v[12:15], v[140:143], v[210:213], v[12:15]
	v_mfma_f32_16x16x32_bf16 v[8:11], v[148:151], v[210:213], v[8:11]
	v_mfma_f32_16x16x32_bf16 v[60:63], v[144:147], v[180:183], v[60:63]
	v_mfma_f32_16x16x32_bf16 v[56:59], v[152:155], v[180:183], v[56:59]
	v_mfma_f32_16x16x32_bf16 v[44:47], v[144:147], v[188:191], v[44:47]
	v_mfma_f32_16x16x32_bf16 v[40:43], v[152:155], v[188:191], v[40:43]
	v_mfma_f32_16x16x32_bf16 v[28:31], v[144:147], v[206:209], v[28:31]
	v_mfma_f32_16x16x32_bf16 v[24:27], v[152:155], v[206:209], v[24:27]
	v_mfma_f32_16x16x32_bf16 v[12:15], v[144:147], v[214:217], v[12:15]
	v_mfma_f32_16x16x32_bf16 v[8:11], v[152:155], v[214:217], v[8:11]
	s_setprio 0
	s_setprio 1
	v_mfma_f32_16x16x32_bf16 v[52:55], v[156:159], v[176:179], v[52:55]
	v_mfma_f32_16x16x32_bf16 v[48:51], v[168:171], v[176:179], v[48:51]
	v_mfma_f32_16x16x32_bf16 v[36:39], v[156:159], v[184:187], v[36:39]
	v_mfma_f32_16x16x32_bf16 v[32:35], v[168:171], v[184:187], v[32:35]
	v_mfma_f32_16x16x32_bf16 v[20:23], v[156:159], v[192:195], v[20:23]
	v_mfma_f32_16x16x32_bf16 v[16:19], v[168:171], v[192:195], v[16:19]
	v_mfma_f32_16x16x32_bf16 v[4:7], v[156:159], v[210:213], v[4:7]
	v_mfma_f32_16x16x32_bf16 v[0:3], v[168:171], v[210:213], v[0:3]
	v_mfma_f32_16x16x32_bf16 v[52:55], v[160:163], v[180:183], v[52:55]
	v_mfma_f32_16x16x32_bf16 v[48:51], v[172:175], v[180:183], v[48:51]
	v_mfma_f32_16x16x32_bf16 v[36:39], v[160:163], v[188:191], v[36:39]
	v_mfma_f32_16x16x32_bf16 v[32:35], v[172:175], v[188:191], v[32:35]
	v_mfma_f32_16x16x32_bf16 v[20:23], v[160:163], v[206:209], v[20:23]
	v_mfma_f32_16x16x32_bf16 v[16:19], v[172:175], v[206:209], v[16:19]
	v_mfma_f32_16x16x32_bf16 v[4:7], v[160:163], v[214:217], v[4:7]
	v_mfma_f32_16x16x32_bf16 v[0:3], v[172:175], v[214:217], v[0:3]
	s_setprio 0
; #define PG8_STAGE(bufoff, gbase, voff) do { _Pragma("unroll") for (int _i = 0; _i < 2; ++_i) \
;         __builtin_amdgcn_global_load_lds((const unsigned*)((const char*)(gbase) + (voff)[_i]), (LAS unsigned*)(lds + (bufoff) + ldsw + _i * 8192), 16, 0, 0); } while (0)
; #define PG8_LDA(dst, b, h) do { _Pragma("unroll") for (int m = 0; m < 4; ++m) _Pragma("unroll") for (int k = 0; k < 2; ++k) dst[m][k] = *(const LAS bf16x8*)(lds + PG8_SA(b, h) + aoff + m * 2048 + k * 1024); } while (0)
; #define PG8_LDB(dst, b, h) do { _Pragma("unroll") for (int n = 0; n < 2; ++n) _Pragma("unroll") for (int k = 0; k < 2; ++k) dst[n][k] = *(const LAS bf16x8*)(lds + PG8_SB(b, h) + boff + n * 2048 + k * 1024); } while (0)
; #define PG8_MMA(ai, bj, At, Bt) do { __builtin_amdgcn_s_setprio(1); _Pragma("unroll") for (int m = 0; m < 4; ++m) _Pragma("unroll") for (int n = 0; n < 2; ++n) _Pragma("unroll") for (int k = 0; k < 2; ++k) \
;         acc[ai][bj][m][n] = __builtin_amdgcn_mfma_f32_16x16x32_bf16(Bt[n][k], At[m][k], acc[ai][bj][m][n], 0, 0, 0); __builtin_amdgcn_s_setprio(0); } while (0)
; #define PG8_WAIT_V(n) asm volatile("s_waitcnt vmcnt(" #n ")" ::: "memory")
; #define PG8_WAIT_L(n) asm volatile("s_waitcnt lgkmcnt(" #n ")" ::: "memory")
; #define PG8_BAR __builtin_amdgcn_s_barrier()
; #define PG8_SCHED __builtin_amdgcn_sched_barrier(0)
; template <class Epi, class Sched>
; __device__ __forceinline__ void gemm_phase(LAS unsigned char* lds, const GemmP g, const Sched& S, const Epi& E, int tid) {
;     ...
;             PG8_LDB(B0, 1, 0); PG8_LDB(B1, 1, 1); PG8_SCHED; PG8_LDA(At, 1, 0); PG8_STAGE(PG8_SA(0, 1), a2 + hstepA, voffA);
;             PG8_WAIT_V(8); PG8_WAIT_L(0); PG8_BAR; PG8_MMA(0, 0, At, B0); PG8_MMA(0, 1, At, B1); PG8_BAR; PG8_SCHED;
.Lsk_cs_2:
	s_barrier
	s_add_i32 s60, 0, 0x18000
	s_add_i32 s61, 0, 0x1c000
	v_add_u32_e32 v152, s60, v166
	v_add_u32_e32 v172, s61, v166
	ds_read_b128 v[140:143], v152
	ds_read_b128 v[144:147], v152 offset:1024
	ds_read_b128 v[148:151], v152 offset:2048
	ds_read_b128 v[152:155], v152 offset:3072
	ds_read_b128 v[156:159], v172
	ds_read_b128 v[160:163], v172 offset:1024
	ds_read_b128 v[168:171], v172 offset:2048
	ds_read_b128 v[172:175], v172 offset:3072
	s_add_u32 s30, s30, 0x40000
	s_addc_u32 s31, s31, 0
	s_mov_b32 m0, s46
	v_lshl_add_u64 v[222:223], s[30:31], 0, v[128:129]
	ds_read_b128 v[176:179], v167 offset:32768
	ds_read_b128 v[180:183], v167 offset:33792
	ds_read_b128 v[184:187], v167 offset:34816
	ds_read_b128 v[188:191], v167 offset:35840
	ds_read_b128 v[192:195], v167 offset:36864
	ds_read_b128 v[206:209], v167 offset:37888
	ds_read_b128 v[210:213], v167 offset:38912
	ds_read_b128 v[214:217], v167 offset:39936
	global_load_lds_dwordx4 v[222:223], off
	v_lshl_add_u64 v[222:223], s[30:31], 0, v[132:133]
	s_mov_b32 m0, s47
	s_nop 0
	global_load_lds_dwordx4 v[222:223], off
	s_waitcnt vmcnt(8)
	s_waitcnt lgkmcnt(0)
	s_barrier
	s_cmp_lg_u32 s32, 0
	s_cbranch_scc1 .Lsk_cs_3
	s_setprio 1
	s_waitcnt lgkmcnt(0)
	v_mfma_f32_16x16x32_bf16 v[124:127], v[140:143], v[176:179], v[124:127]
	v_mfma_f32_16x16x32_bf16 v[120:123], v[148:151], v[176:179], v[120:123]
	v_mfma_f32_16x16x32_bf16 v[108:111], v[140:143], v[184:187], v[108:111]
	v_mfma_f32_16x16x32_bf16 v[104:107], v[148:151], v[184:187], v[104:107]
	v_mfma_f32_16x16x32_bf16 v[92:95], v[140:143], v[192:195], v[92:95]
	v_mfma_f32_16x16x32_bf16 v[88:91], v[148:151], v[192:195], v[88:91]
	v_mfma_f32_16x16x32_bf16 v[76:79], v[140:143], v[210:213], v[76:79]
	v_mfma_f32_16x16x32_bf16 v[72:75], v[148:151], v[210:213], v[72:75]
	v_mfma_f32_16x16x32_bf16 v[124:127], v[144:147], v[180:183], v[124:127]
	v_mfma_f32_16x16x32_bf16 v[120:123], v[152:155], v[180:183], v[120:123]
	v_mfma_f32_16x16x32_bf16 v[108:111], v[144:147], v[188:191], v[108:111]
	v_mfma_f32_16x16x32_bf16 v[104:107], v[152:155], v[188:191], v[104:107]
	v_mfma_f32_16x16x32_bf16 v[92:95], v[144:147], v[206:209], v[92:95]
	v_mfma_f32_16x16x32_bf16 v[88:91], v[152:155], v[206:209], v[88:91]
	v_mfma_f32_16x16x32_bf16 v[76:79], v[144:147], v[214:217], v[76:79]
	v_mfma_f32_16x16x32_bf16 v[72:75], v[152:155], v[214:217], v[72:75]
	s_setprio 0
	s_setprio 1
	v_mfma_f32_16x16x32_bf16 v[116:119], v[156:159], v[176:179], v[116:119]
	v_mfma_f32_16x16x32_bf16 v[112:115], v[168:171], v[176:179], v[112:115]
	v_mfma_f32_16x16x32_bf16 v[100:103], v[156:159], v[184:187], v[100:103]
	v_mfma_f32_16x16x32_bf16 v[96:99], v[168:171], v[184:187], v[96:99]
	v_mfma_f32_16x16x32_bf16 v[84:87], v[156:159], v[192:195], v[84:87]
	v_mfma_f32_16x16x32_bf16 v[80:83], v[168:171], v[192:195], v[80:83]
	v_mfma_f32_16x16x32_bf16 v[68:71], v[156:159], v[210:213], v[68:71]
	v_mfma_f32_16x16x32_bf16 v[64:67], v[168:171], v[210:213], v[64:67]
	v_mfma_f32_16x16x32_bf16 v[116:119], v[160:163], v[180:183], v[116:119]
	v_mfma_f32_16x16x32_bf16 v[112:115], v[172:175], v[180:183], v[112:115]
	v_mfma_f32_16x16x32_bf16 v[100:103], v[160:163], v[188:191], v[100:103]
	v_mfma_f32_16x16x32_bf16 v[96:99], v[172:175], v[188:191], v[96:99]
	v_mfma_f32_16x16x32_bf16 v[84:87], v[160:163], v[206:209], v[84:87]
	v_mfma_f32_16x16x32_bf16 v[80:83], v[172:175], v[206:209], v[80:83]
	v_mfma_f32_16x16x32_bf16 v[68:71], v[160:163], v[214:217], v[68:71]
	v_mfma_f32_16x16x32_bf16 v[64:67], v[172:175], v[214:217], v[64:67]
	s_setprio 0
; #define PG8_STAGE(bufoff, gbase, voff) do { _Pragma("unroll") for (int _i = 0; _i < 2; ++_i) \
;         __builtin_amdgcn_global_load_lds((const unsigned*)((const char*)(gbase) + (voff)[_i]), (LAS unsigned*)(lds + (bufoff) + ldsw + _i * 8192), 16, 0, 0); } while (0)
; #define PG8_LDA(dst, b, h) do { _Pragma("unroll") for (int m = 0; m < 4; ++m) _Pragma("unroll") for (int k = 0; k < 2; ++k) dst[m][k] = *(const LAS bf16x8*)(lds + PG8_SA(b, h) + aoff + m * 2048 + k * 1024); } while (0)
; #define PG8_MMA(ai, bj, At, Bt) do { __builtin_amdgcn_s_setprio(1); _Pragma("unroll") for (int m = 0; m < 4; ++m) _Pragma("unroll") for (int n = 0; n < 2; ++n) _Pragma("unroll") for (int k = 0; k < 2; ++k) \
;         acc[ai][bj][m][n] = __builtin_amdgcn_mfma_f32_16x16x32_bf16(Bt[n][k], At[m][k], acc[ai][bj][m][n], 0, 0, 0); __builtin_amdgcn_s_setprio(0); } while (0)
; #define PG8_WAIT_V(n) asm volatile("s_waitcnt vmcnt(" #n ")" ::: "memory")
; #define PG8_WAIT_L(n) asm volatile("s_waitcnt lgkmcnt(" #n ")" ::: "memory")
; #define PG8_BAR __builtin_amdgcn_s_barrier()
; #define PG8_SCHED __builtin_amdgcn_sched_barrier(0)
; template <class Epi, class Sched>
; __device__ __forceinline__ void gemm_phase(LAS unsigned char* lds, const GemmP g, const Sched& S, const Epi& E, int tid) {
;     ...
;             PG8_LDA(At, 1, 1); PG8_STAGE(PG8_SB(1, 0), b3, voffB); PG8_STAGE(PG8_SB(1, 1), b3 + hstepB, voffB); PG8_STAGE(PG8_SA(1, 0), a3, voffA);
;             PG8_WAIT_V(8); PG8_WAIT_L(0); PG8_BAR; PG8_MMA(1, 0, At, B0); PG8_MMA(1, 1, At, B1); PG8_BAR; PG8_SCHED;
;         }
;         if (wr == 0) PG8_BAR;
.Lsk_cs_3:
	s_barrier
	s_add_i32 s30, s60, s41
	v_lshl_add_u64 v[164:165], v[164:165], 0, s[80:81]
	s_mov_b32 m0, s30
	ds_read_b128 v[176:179], v167 offset:49152
	ds_read_b128 v[180:183], v167 offset:50176
	ds_read_b128 v[184:187], v167 offset:51200
	ds_read_b128 v[188:191], v167 offset:52224
	ds_read_b128 v[192:195], v167 offset:53248
	ds_read_b128 v[206:209], v167 offset:54272
	ds_read_b128 v[210:213], v167 offset:55296
	ds_read_b128 v[214:217], v167 offset:56320
	global_load_lds_dwordx4 v[164:165], off
	s_add_i32 m0, s30, 0x2000
	s_add_u32 s28, s28, 0x40080
	v_lshl_add_u64 v[164:165], v[198:199], 0, s[80:81]
	s_addc_u32 s29, s29, 0
	s_add_i32 s30, s61, s41
	global_load_lds_dwordx4 v[164:165], off
	v_lshl_add_u64 v[164:165], s[28:29], 0, v[130:131]
	s_mov_b32 m0, s30
	s_nop 0
	global_load_lds_dwordx4 v[164:165], off
	v_lshl_add_u64 v[164:165], s[28:29], 0, v[134:135]
	s_add_i32 m0, s30, 0x2000
	s_nop 0
	global_load_lds_dwordx4 v[164:165], off
	v_lshl_add_u64 v[164:165], v[200:201], 0, s[80:81]
	s_mov_b32 m0, s51
	s_nop 0
	global_load_lds_dwordx4 v[164:165], off
	v_lshl_add_u64 v[164:165], v[220:221], 0, s[80:81]
	s_mov_b32 m0, s52
	s_nop 0
	global_load_lds_dwordx4 v[164:165], off
	s_waitcnt vmcnt(8)
	s_waitcnt lgkmcnt(0)
	s_barrier
	s_cmp_lg_u32 s98, 0
	s_cbranch_scc1 .Lsk_cs_4
	s_setprio 1
	s_waitcnt lgkmcnt(0)
	v_mfma_f32_16x16x32_bf16 v[60:63], v[140:143], v[176:179], v[60:63]
	v_mfma_f32_16x16x32_bf16 v[56:59], v[148:151], v[176:179], v[56:59]
	v_mfma_f32_16x16x32_bf16 v[44:47], v[140:143], v[184:187], v[44:47]
	v_mfma_f32_16x16x32_bf16 v[40:43], v[148:151], v[184:187], v[40:43]
	v_mfma_f32_16x16x32_bf16 v[28:31], v[140:143], v[192:195], v[28:31]
	v_mfma_f32_16x16x32_bf16 v[24:27], v[148:151], v[192:195], v[24:27]
	v_mfma_f32_16x16x32_bf16 v[12:15], v[140:143], v[210:213], v[12:15]
	v_mfma_f32_16x16x32_bf16 v[8:11], v[148:151], v[210:213], v[8:11]
	v_mfma_f32_16x16x32_bf16 v[60:63], v[144:147], v[180:183], v[60:63]
	v_mfma_f32_16x16x32_bf16 v[56:59], v[152:155], v[180:183], v[56:59]
	v_mfma_f32_16x16x32_bf16 v[44:47], v[144:147], v[188:191], v[44:47]
	v_mfma_f32_16x16x32_bf16 v[40:43], v[152:155], v[188:191], v[40:43]
	v_mfma_f32_16x16x32_bf16 v[28:31], v[144:147], v[206:209], v[28:31]
	v_mfma_f32_16x16x32_bf16 v[24:27], v[152:155], v[206:209], v[24:27]
	v_mfma_f32_16x16x32_bf16 v[12:15], v[144:147], v[214:217], v[12:15]
	v_mfma_f32_16x16x32_bf16 v[8:11], v[152:155], v[214:217], v[8:11]
	s_setprio 0
	s_setprio 1
	v_mfma_f32_16x16x32_bf16 v[52:55], v[156:159], v[176:179], v[52:55]
	v_mfma_f32_16x16x32_bf16 v[48:51], v[168:171], v[176:179], v[48:51]
	v_mfma_f32_16x16x32_bf16 v[36:39], v[156:159], v[184:187], v[36:39]
	v_mfma_f32_16x16x32_bf16 v[32:35], v[168:171], v[184:187], v[32:35]
	v_mfma_f32_16x16x32_bf16 v[20:23], v[156:159], v[192:195], v[20:23]
	v_mfma_f32_16x16x32_bf16 v[16:19], v[168:171], v[192:195], v[16:19]
	v_mfma_f32_16x16x32_bf16 v[4:7], v[156:159], v[210:213], v[4:7]
	v_mfma_f32_16x16x32_bf16 v[0:3], v[168:171], v[210:213], v[0:3]
	v_mfma_f32_16x16x32_bf16 v[52:55], v[160:163], v[180:183], v[52:55]
	v_mfma_f32_16x16x32_bf16 v[48:51], v[172:175], v[180:183], v[48:51]
	v_mfma_f32_16x16x32_bf16 v[36:39], v[160:163], v[188:191], v[36:39]
	v_mfma_f32_16x16x32_bf16 v[32:35], v[172:175], v[188:191], v[32:35]
	v_mfma_f32_16x16x32_bf16 v[20:23], v[160:163], v[206:209], v[20:23]
	v_mfma_f32_16x16x32_bf16 v[16:19], v[172:175], v[206:209], v[16:19]
	v_mfma_f32_16x16x32_bf16 v[4:7], v[160:163], v[214:217], v[4:7]
	v_mfma_f32_16x16x32_bf16 v[0:3], v[172:175], v[214:217], v[0:3]
	s_setprio 0
.Lsk_cs_4:
	s_barrier
	s_add_i32 s57, s57, 2
	s_add_u32 s5, s5, 0x100
	s_addc_u32 s56, s56, 0
	s_add_u32 s26, s26, 0x100
	s_addc_u32 s27, s27, 0
	s_cmp_gt_u32 s57, 13
	s_cbranch_scc0 .LBB0_996
	s_and_b64 vcc, exec, s[16:17]
	s_cbranch_vccz .LBB0_999
	s_barrier

; #define PG8_BAR __builtin_amdgcn_s_barrier()
; template <class Epi, class Sched>
; __device__ __forceinline__ void gemm_phase(LAS unsigned char* lds, const GemmP g, const Sched& S, const Epi& E, int tid) {
;     ...
; #pragma unroll
;         for (int a = 0; a < 2; ++a)
; #pragma unroll
;             for (int b = 0; b < 2; ++b)
; #pragma unroll
;                 for (int m = 0; m < 4; ++m)
; #pragma unroll
;                     for (int n = 0; n < 2; ++n) acc[a][b][m][n] = (f32x4){0.f, 0.f, 0.f, 0.f};
;         cur = nxt; cA = nA; cB = nB; ++ui;
;         if (wr == 1) PG8_BAR;
;     __device__ __forceinline__ bool next(int i, Unit& u) const {
;         const int L = i * G + c; if (L >= 1024 + 128) return false;
;         int row0, bb, hp;
;         if (L < 1024) { const int pm = L >> 2; hp = L & 3; row0 = pm * BM; bb = pm >> 4; u.vlo = 0; u.vhi = 0x7fffffff; }
;         else { const int s = L - 1024, b = s >> 2; hp = s & 3; const int r = MP + DSEQ * b; row0 = r < M - BM ? r : M - BM; bb = NB + b; u.vlo = r; u.vhi = r + DSEQ; }
.LBB0_1162:
	s_add_u32 s12, s8, 0x100
	s_addc_u32 s13, s9, 0
	s_add_u32 s6, s6, 0x40080
	v_mov_b32_e32 v0, 0
	s_addc_u32 s7, s7, 0
	s_mov_b32 s14, -2
	s_waitcnt lgkmcnt(0)
	v_mov_b32_e32 v1, v0
	v_mov_b32_e32 v2, v0
	v_mov_b32_e32 v3, v0
	v_mov_b32_e32 v4, v0
	v_mov_b32_e32 v5, v0
	v_mov_b32_e32 v6, v0
	v_mov_b32_e32 v7, v0
	v_mov_b32_e32 v8, v0
	v_mov_b32_e32 v9, v0
	v_mov_b32_e32 v10, v0
	v_mov_b32_e32 v11, v0
	v_mov_b32_e32 v12, v0
	v_mov_b32_e32 v13, v0
	v_mov_b32_e32 v14, v0
	v_mov_b32_e32 v15, v0
	v_mov_b32_e32 v16, v0
	v_mov_b32_e32 v17, v0
	v_mov_b32_e32 v18, v0
	v_mov_b32_e32 v19, v0
	v_mov_b32_e32 v20, v0
	v_mov_b32_e32 v21, v0
	v_mov_b32_e32 v22, v0
	v_mov_b32_e32 v23, v0
	v_mov_b32_e32 v24, v0
	v_mov_b32_e32 v25, v0
	v_mov_b32_e32 v26, v0
	v_mov_b32_e32 v27, v0
	v_mov_b32_e32 v28, v0
	v_mov_b32_e32 v29, v0
	v_mov_b32_e32 v30, v0
	v_mov_b32_e32 v31, v0
	v_mov_b32_e32 v56, v0
	v_mov_b32_e32 v57, v0
	v_mov_b32_e32 v58, v0
	v_mov_b32_e32 v59, v0
	v_mov_b32_e32 v64, v0
	v_mov_b32_e32 v65, v0
	v_mov_b32_e32 v66, v0
	v_mov_b32_e32 v67, v0
	v_mov_b32_e32 v72, v0
	v_mov_b32_e32 v73, v0
	v_mov_b32_e32 v74, v0
	v_mov_b32_e32 v75, v0
	v_mov_b32_e32 v76, v0
	v_mov_b32_e32 v77, v0
	v_mov_b32_e32 v78, v0
	v_mov_b32_e32 v79, v0
	v_mov_b32_e32 v80, v0
	v_mov_b32_e32 v81, v0
	v_mov_b32_e32 v82, v0
	v_mov_b32_e32 v83, v0
	v_mov_b32_e32 v84, v0
	v_mov_b32_e32 v85, v0
	v_mov_b32_e32 v86, v0
	v_mov_b32_e32 v87, v0
	v_mov_b32_e32 v88, v0
	v_mov_b32_e32 v89, v0
	v_mov_b32_e32 v90, v0
	v_mov_b32_e32 v91, v0
	v_mov_b32_e32 v92, v0
	v_mov_b32_e32 v93, v0
	v_mov_b32_e32 v94, v0
	v_mov_b32_e32 v95, v0
	v_mov_b32_e32 v32, v0
	v_mov_b32_e32 v33, v0
	v_mov_b32_e32 v34, v0
	v_mov_b32_e32 v35, v0
	v_mov_b32_e32 v36, v0
	v_mov_b32_e32 v37, v0
	v_mov_b32_e32 v38, v0
	v_mov_b32_e32 v39, v0
	v_mov_b32_e32 v40, v0
	v_mov_b32_e32 v41, v0
	v_mov_b32_e32 v42, v0
	v_mov_b32_e32 v43, v0
	v_mov_b32_e32 v44, v0
	v_mov_b32_e32 v45, v0
	v_mov_b32_e32 v46, v0
	v_mov_b32_e32 v47, v0
	v_mov_b32_e32 v48, v0
	v_mov_b32_e32 v49, v0
	v_mov_b32_e32 v50, v0
	v_mov_b32_e32 v51, v0
	v_mov_b32_e32 v52, v0
	v_mov_b32_e32 v53, v0
	v_mov_b32_e32 v54, v0
	v_mov_b32_e32 v55, v0
	v_mov_b32_e32 v60, v0
	v_mov_b32_e32 v61, v0
	v_mov_b32_e32 v62, v0
	v_mov_b32_e32 v63, v0
	v_mov_b32_e32 v68, v0
	v_mov_b32_e32 v69, v0
	v_mov_b32_e32 v70, v0
	v_mov_b32_e32 v71, v0
	v_mov_b32_e32 v96, v0
	v_mov_b32_e32 v97, v0
	v_mov_b32_e32 v98, v0
	v_mov_b32_e32 v99, v0
	v_mov_b32_e32 v100, v0
	v_mov_b32_e32 v101, v0
	v_mov_b32_e32 v102, v0
	v_mov_b32_e32 v103, v0
	v_mov_b32_e32 v104, v0
	v_mov_b32_e32 v105, v0
	v_mov_b32_e32 v106, v0
	v_mov_b32_e32 v107, v0
	v_mov_b32_e32 v108, v0
	v_mov_b32_e32 v109, v0
	v_mov_b32_e32 v110, v0
	v_mov_b32_e32 v111, v0
	v_mov_b32_e32 v112, v0
	v_mov_b32_e32 v113, v0
	v_mov_b32_e32 v114, v0
	v_mov_b32_e32 v115, v0
	v_mov_b32_e32 v116, v0
	v_mov_b32_e32 v117, v0
	v_mov_b32_e32 v118, v0
	v_mov_b32_e32 v119, v0
	v_mov_b32_e32 v128, v0
	v_mov_b32_e32 v129, v0
	v_mov_b32_e32 v130, v0
	v_mov_b32_e32 v131, v0
	v_mov_b32_e32 v120, v0
	v_mov_b32_e32 v121, v0
	v_mov_b32_e32 v122, v0
	v_mov_b32_e32 v123, v0
	s_sub_i32 s32, s41, s4
	s_bfe_u32 s98, s32, 0x10006
	s_bfe_u32 s32, s32, 0x10007
	s_cmp_lg_u64 s[2:3], 0
	s_cselect_b32 s99, 1, 0
	s_xor_b32 s98, s98, s99
	s_or_b32 s99, s98, s32
	s_xor_b32 s32, s32, 1
	s_or_b32 s98, s98, s32
	s_cmp_eq_u32 s40, 0x7fffffff
	s_cselect_b32 s32, 0, s99
	s_cselect_b32 s98, 0, s98

; #define PG8_STAGE(bufoff, gbase, voff) do { _Pragma("unroll") for (int _i = 0; _i < 2; ++_i) \
;         __builtin_amdgcn_global_load_lds((const unsigned*)((const char*)(gbase) + (voff)[_i]), (LAS unsigned*)(lds + (bufoff) + ldsw + _i * 8192), 16, 0, 0); } while (0)
; #define PG8_LDA(dst, b, h) do { _Pragma("unroll") for (int m = 0; m < 4; ++m) _Pragma("unroll") for (int k = 0; k < 2; ++k) dst[m][k] = *(const LAS bf16x8*)(lds + PG8_SA(b, h) + aoff + m * 2048 + k * 1024); } while (0)
; #define PG8_MMA(ai, bj, At, Bt) do { __builtin_amdgcn_s_setprio(1); _Pragma("unroll") for (int m = 0; m < 4; ++m) _Pragma("unroll") for (int n = 0; n < 2; ++n) _Pragma("unroll") for (int k = 0; k < 2; ++k) \
;         acc[ai][bj][m][n] = __builtin_amdgcn_mfma_f32_16x16x32_bf16(Bt[n][k], At[m][k], acc[ai][bj][m][n], 0, 0, 0); __builtin_amdgcn_s_setprio(0); } while (0)
; #define PG8_WAIT_V(n) asm volatile("s_waitcnt vmcnt(" #n ")" ::: "memory")
; #define PG8_WAIT_L(n) asm volatile("s_waitcnt lgkmcnt(" #n ")" ::: "memory")
; #define PG8_BAR __builtin_amdgcn_s_barrier()
; #define PG8_SCHED __builtin_amdgcn_sched_barrier(0)
; template <class Epi, class Sched>
; __device__ __forceinline__ void gemm_phase(LAS unsigned char* lds, const GemmP g, const Sched& S, const Epi& E, int tid) {
;     ...
;             PG8_WAIT_V(8); PG8_WAIT_L(0); PG8_BAR; PG8_MMA(0, 0, At, B0); PG8_MMA(0, 1, At, B1); PG8_BAR; PG8_SCHED;
;             PG8_LDA(At, 0, 1); PG8_STAGE(PG8_SB(0, 0), b2, voffB); PG8_STAGE(PG8_SB(0, 1), b2 + hstepB, voffB); PG8_STAGE(PG8_SA(0, 0), a2, voffA);
;             PG8_WAIT_V(8); PG8_WAIT_L(0); PG8_BAR; PG8_MMA(1, 0, At, B0); PG8_MMA(1, 1, At, B1); PG8_BAR; PG8_SCHED;
.Lfirstit_4:
	s_waitcnt lgkmcnt(0)
	s_barrier
	s_cmp_lg_u32 s32, 0
	s_cbranch_scc1 .Lsk_co_1
	s_setprio 1
	s_waitcnt lgkmcnt(0)
	v_mfma_f32_16x16x32_bf16 v[120:123], v[124:127], v[160:163], v[120:123]
	v_mfma_f32_16x16x32_bf16 v[128:131], v[136:139], v[160:163], v[128:131]
	v_mfma_f32_16x16x32_bf16 v[116:119], v[124:127], v[168:171], v[116:119]
	v_mfma_f32_16x16x32_bf16 v[112:115], v[136:139], v[168:171], v[112:115]
	v_mfma_f32_16x16x32_bf16 v[108:111], v[124:127], v[176:179], v[108:111]
	v_mfma_f32_16x16x32_bf16 v[104:107], v[136:139], v[176:179], v[104:107]
	v_mfma_f32_16x16x32_bf16 v[100:103], v[124:127], v[184:187], v[100:103]
	v_mfma_f32_16x16x32_bf16 v[96:99], v[136:139], v[184:187], v[96:99]
	v_mfma_f32_16x16x32_bf16 v[120:123], v[132:135], v[164:167], v[120:123]
	v_mfma_f32_16x16x32_bf16 v[128:131], v[140:143], v[164:167], v[128:131]
	v_mfma_f32_16x16x32_bf16 v[116:119], v[132:135], v[172:175], v[116:119]
	v_mfma_f32_16x16x32_bf16 v[112:115], v[140:143], v[172:175], v[112:115]
	v_mfma_f32_16x16x32_bf16 v[108:111], v[132:135], v[180:183], v[108:111]
	v_mfma_f32_16x16x32_bf16 v[104:107], v[140:143], v[180:183], v[104:107]
	v_mfma_f32_16x16x32_bf16 v[100:103], v[132:135], v[210:213], v[100:103]
	v_mfma_f32_16x16x32_bf16 v[96:99], v[140:143], v[210:213], v[96:99]
	s_setprio 0
	s_setprio 1
	v_mfma_f32_16x16x32_bf16 v[68:71], v[144:147], v[160:163], v[68:71]
	v_mfma_f32_16x16x32_bf16 v[60:63], v[152:155], v[160:163], v[60:63]
	v_mfma_f32_16x16x32_bf16 v[52:55], v[144:147], v[168:171], v[52:55]
	v_mfma_f32_16x16x32_bf16 v[48:51], v[152:155], v[168:171], v[48:51]
	v_mfma_f32_16x16x32_bf16 v[44:47], v[144:147], v[176:179], v[44:47]
	v_mfma_f32_16x16x32_bf16 v[40:43], v[152:155], v[176:179], v[40:43]
	v_mfma_f32_16x16x32_bf16 v[36:39], v[144:147], v[184:187], v[36:39]
	v_mfma_f32_16x16x32_bf16 v[32:35], v[152:155], v[184:187], v[32:35]
	v_mfma_f32_16x16x32_bf16 v[68:71], v[148:151], v[164:167], v[68:71]
	v_mfma_f32_16x16x32_bf16 v[60:63], v[156:159], v[164:167], v[60:63]
	v_mfma_f32_16x16x32_bf16 v[52:55], v[148:151], v[172:175], v[52:55]
	v_mfma_f32_16x16x32_bf16 v[48:51], v[156:159], v[172:175], v[48:51]
	v_mfma_f32_16x16x32_bf16 v[44:47], v[148:151], v[180:183], v[44:47]
	v_mfma_f32_16x16x32_bf16 v[40:43], v[156:159], v[180:183], v[40:43]
	v_mfma_f32_16x16x32_bf16 v[36:39], v[148:151], v[210:213], v[36:39]
	v_mfma_f32_16x16x32_bf16 v[32:35], v[156:159], v[210:213], v[32:35]
	s_setprio 0
.Lsk_co_1:
	s_barrier
	s_add_i32 s15, s15, s62
	v_lshl_add_u64 v[198:199], s[8:9], 0, v[190:191]
	s_mov_b32 m0, s15
	ds_read_b128 v[160:163], v215 offset:16384
	ds_read_b128 v[164:167], v215 offset:17408
	ds_read_b128 v[168:171], v215 offset:18432
	ds_read_b128 v[172:175], v215 offset:19456
	ds_read_b128 v[176:179], v215 offset:20480
	ds_read_b128 v[180:183], v215 offset:21504
	ds_read_b128 v[184:187], v215 offset:22528
	ds_read_b128 v[210:213], v215 offset:23552
	global_load_lds_dwordx4 v[198:199], off
	s_add_i32 m0, s15, 0x2000
	s_add_u32 s16, s8, 0x40000
	v_lshl_add_u64 v[200:201], s[8:9], 0, v[194:195]
	s_addc_u32 s17, s9, 0
	s_add_i32 s15, s18, s62
	global_load_lds_dwordx4 v[200:201], off
	v_lshl_add_u64 v[216:217], s[16:17], 0, v[190:191]
	s_mov_b32 m0, s15
	v_lshl_add_u64 v[220:221], s[10:11], 0, v[192:193]
	global_load_lds_dwordx4 v[216:217], off
	v_lshl_add_u64 v[216:217], s[16:17], 0, v[194:195]
	s_add_i32 m0, s15, 0x2000
	s_nop 0
	global_load_lds_dwordx4 v[216:217], off
	v_lshl_add_u64 v[216:217], s[10:11], 0, v[188:189]
	s_mov_b32 m0, s63
	s_nop 0
	global_load_lds_dwordx4 v[216:217], off
	s_mov_b32 m0, s68
	s_nop 0
	global_load_lds_dwordx4 v[220:221], off
	s_waitcnt vmcnt(8)
	s_waitcnt lgkmcnt(0)
	s_barrier
	s_cmp_lg_u32 s98, 0
	s_cbranch_scc1 .Lsk_co_2
	s_setprio 1
	s_waitcnt lgkmcnt(0)
	v_mfma_f32_16x16x32_bf16 v[92:95], v[124:127], v[160:163], v[92:95]
	v_mfma_f32_16x16x32_bf16 v[88:91], v[136:139], v[160:163], v[88:91]
	v_mfma_f32_16x16x32_bf16 v[84:87], v[124:127], v[168:171], v[84:87]
	v_mfma_f32_16x16x32_bf16 v[80:83], v[136:139], v[168:171], v[80:83]
	v_mfma_f32_16x16x32_bf16 v[76:79], v[124:127], v[176:179], v[76:79]
	v_mfma_f32_16x16x32_bf16 v[72:75], v[136:139], v[176:179], v[72:75]
	v_mfma_f32_16x16x32_bf16 v[64:67], v[124:127], v[184:187], v[64:67]
	v_mfma_f32_16x16x32_bf16 v[56:59], v[136:139], v[184:187], v[56:59]
	v_mfma_f32_16x16x32_bf16 v[92:95], v[132:135], v[164:167], v[92:95]
	v_mfma_f32_16x16x32_bf16 v[88:91], v[140:143], v[164:167], v[88:91]
	v_mfma_f32_16x16x32_bf16 v[84:87], v[132:135], v[172:175], v[84:87]
	v_mfma_f32_16x16x32_bf16 v[80:83], v[140:143], v[172:175], v[80:83]
	v_mfma_f32_16x16x32_bf16 v[76:79], v[132:135], v[180:183], v[76:79]
	v_mfma_f32_16x16x32_bf16 v[72:75], v[140:143], v[180:183], v[72:75]
	v_mfma_f32_16x16x32_bf16 v[64:67], v[132:135], v[210:213], v[64:67]
	v_mfma_f32_16x16x32_bf16 v[56:59], v[140:143], v[210:213], v[56:59]
	s_setprio 0
	s_setprio 1
	v_mfma_f32_16x16x32_bf16 v[28:31], v[144:147], v[160:163], v[28:31]
	v_mfma_f32_16x16x32_bf16 v[24:27], v[152:155], v[160:163], v[24:27]
	v_mfma_f32_16x16x32_bf16 v[20:23], v[144:147], v[168:171], v[20:23]
	v_mfma_f32_16x16x32_bf16 v[16:19], v[152:155], v[168:171], v[16:19]
	v_mfma_f32_16x16x32_bf16 v[12:15], v[144:147], v[176:179], v[12:15]
	v_mfma_f32_16x16x32_bf16 v[8:11], v[152:155], v[176:179], v[8:11]
	v_mfma_f32_16x16x32_bf16 v[4:7], v[144:147], v[184:187], v[4:7]
	v_mfma_f32_16x16x32_bf16 v[0:3], v[152:155], v[184:187], v[0:3]
	v_mfma_f32_16x16x32_bf16 v[28:31], v[148:151], v[164:167], v[28:31]
	v_mfma_f32_16x16x32_bf16 v[24:27], v[156:159], v[164:167], v[24:27]
	v_mfma_f32_16x16x32_bf16 v[20:23], v[148:151], v[172:175], v[20:23]
	v_mfma_f32_16x16x32_bf16 v[16:19], v[156:159], v[172:175], v[16:19]
	v_mfma_f32_16x16x32_bf16 v[12:15], v[148:151], v[180:183], v[12:15]
	v_mfma_f32_16x16x32_bf16 v[8:11], v[156:159], v[180:183], v[8:11]
	v_mfma_f32_16x16x32_bf16 v[4:7], v[148:151], v[210:213], v[4:7]
	v_mfma_f32_16x16x32_bf16 v[0:3], v[156:159], v[210:213], v[0:3]
	s_setprio 0
; #define PG8_STAGE(bufoff, gbase, voff) do { _Pragma("unroll") for (int _i = 0; _i < 2; ++_i) \
;         __builtin_amdgcn_global_load_lds((const unsigned*)((const char*)(gbase) + (voff)[_i]), (LAS unsigned*)(lds + (bufoff) + ldsw + _i * 8192), 16, 0, 0); } while (0)
; #define PG8_LDA(dst, b, h) do { _Pragma("unroll") for (int m = 0; m < 4; ++m) _Pragma("unroll") for (int k = 0; k < 2; ++k) dst[m][k] = *(const LAS bf16x8*)(lds + PG8_SA(b, h) + aoff + m * 2048 + k * 1024); } while (0)
; #define PG8_LDB(dst, b, h) do { _Pragma("unroll") for (int n = 0; n < 2; ++n) _Pragma("unroll") for (int k = 0; k < 2; ++k) dst[n][k] = *(const LAS bf16x8*)(lds + PG8_SB(b, h) + boff + n * 2048 + k * 1024); } while (0)
; #define PG8_MMA(ai, bj, At, Bt) do { __builtin_amdgcn_s_setprio(1); _Pragma("unroll") for (int m = 0; m < 4; ++m) _Pragma("unroll") for (int n = 0; n < 2; ++n) _Pragma("unroll") for (int k = 0; k < 2; ++k) \
;         acc[ai][bj][m][n] = __builtin_amdgcn_mfma_f32_16x16x32_bf16(Bt[n][k], At[m][k], acc[ai][bj][m][n], 0, 0, 0); __builtin_amdgcn_s_setprio(0); } while (0)
; #define PG8_WAIT_V(n) asm volatile("s_waitcnt vmcnt(" #n ")" ::: "memory")
; #define PG8_WAIT_L(n) asm volatile("s_waitcnt lgkmcnt(" #n ")" ::: "memory")
; #define PG8_BAR __builtin_amdgcn_s_barrier()
; #define PG8_SCHED __builtin_amdgcn_sched_barrier(0)
; template <class Epi, class Sched>
; __device__ __forceinline__ void gemm_phase(LAS unsigned char* lds, const GemmP g, const Sched& S, const Epi& E, int tid) {
;     ...
;             PG8_LDB(B0, 1, 0); PG8_LDB(B1, 1, 1); PG8_SCHED; PG8_LDA(At, 1, 0); PG8_STAGE(PG8_SA(0, 1), a2 + hstepA, voffA);
;             PG8_WAIT_V(8); PG8_WAIT_L(0); PG8_BAR; PG8_MMA(0, 0, At, B0); PG8_MMA(0, 1, At, B1); PG8_BAR; PG8_SCHED;
.Lsk_co_2:
	s_barrier
	s_add_i32 s15, 0, 0x18000
	s_add_i32 s16, 0, 0x1c000
	v_add_u32_e32 v140, s15, v214
	v_add_u32_e32 v156, s16, v214
	ds_read_b128 v[124:127], v140
	ds_read_b128 v[132:135], v140 offset:1024
	ds_read_b128 v[136:139], v140 offset:2048
	ds_read_b128 v[140:143], v140 offset:3072
	ds_read_b128 v[144:147], v156
	ds_read_b128 v[148:151], v156 offset:1024
	ds_read_b128 v[152:155], v156 offset:2048
	ds_read_b128 v[156:159], v156 offset:3072
	s_add_u32 s10, s10, 0x40000
	s_addc_u32 s11, s11, 0
	s_mov_b32 m0, s69
	v_lshl_add_u64 v[222:223], s[10:11], 0, v[188:189]
	ds_read_b128 v[160:163], v215 offset:32768
	ds_read_b128 v[164:167], v215 offset:33792
	ds_read_b128 v[168:171], v215 offset:34816
	ds_read_b128 v[172:175], v215 offset:35840
	ds_read_b128 v[176:179], v215 offset:36864
	ds_read_b128 v[180:183], v215 offset:37888
	ds_read_b128 v[184:187], v215 offset:38912
	ds_read_b128 v[210:213], v215 offset:39936
	global_load_lds_dwordx4 v[222:223], off
	v_lshl_add_u64 v[222:223], s[10:11], 0, v[192:193]
	s_mov_b32 m0, s88
	s_nop 0
	global_load_lds_dwordx4 v[222:223], off
	s_waitcnt vmcnt(8)
	s_waitcnt lgkmcnt(0)
	s_barrier
	s_cmp_lg_u32 s32, 0
	s_cbranch_scc1 .Lsk_co_3
	s_setprio 1
	s_waitcnt lgkmcnt(0)
	v_mfma_f32_16x16x32_bf16 v[120:123], v[124:127], v[160:163], v[120:123]
	v_mfma_f32_16x16x32_bf16 v[128:131], v[136:139], v[160:163], v[128:131]
	v_mfma_f32_16x16x32_bf16 v[116:119], v[124:127], v[168:171], v[116:119]
	v_mfma_f32_16x16x32_bf16 v[112:115], v[136:139], v[168:171], v[112:115]
	v_mfma_f32_16x16x32_bf16 v[108:111], v[124:127], v[176:179], v[108:111]
	v_mfma_f32_16x16x32_bf16 v[104:107], v[136:139], v[176:179], v[104:107]
	v_mfma_f32_16x16x32_bf16 v[100:103], v[124:127], v[184:187], v[100:103]
	v_mfma_f32_16x16x32_bf16 v[96:99], v[136:139], v[184:187], v[96:99]
	v_mfma_f32_16x16x32_bf16 v[120:123], v[132:135], v[164:167], v[120:123]
	v_mfma_f32_16x16x32_bf16 v[128:131], v[140:143], v[164:167], v[128:131]
	v_mfma_f32_16x16x32_bf16 v[116:119], v[132:135], v[172:175], v[116:119]
	v_mfma_f32_16x16x32_bf16 v[112:115], v[140:143], v[172:175], v[112:115]
	v_mfma_f32_16x16x32_bf16 v[108:111], v[132:135], v[180:183], v[108:111]
	v_mfma_f32_16x16x32_bf16 v[104:107], v[140:143], v[180:183], v[104:107]
	v_mfma_f32_16x16x32_bf16 v[100:103], v[132:135], v[210:213], v[100:103]
	v_mfma_f32_16x16x32_bf16 v[96:99], v[140:143], v[210:213], v[96:99]
	s_setprio 0
	s_setprio 1
	v_mfma_f32_16x16x32_bf16 v[68:71], v[144:147], v[160:163], v[68:71]
	v_mfma_f32_16x16x32_bf16 v[60:63], v[152:155], v[160:163], v[60:63]
	v_mfma_f32_16x16x32_bf16 v[52:55], v[144:147], v[168:171], v[52:55]
	v_mfma_f32_16x16x32_bf16 v[48:51], v[152:155], v[168:171], v[48:51]
	v_mfma_f32_16x16x32_bf16 v[44:47], v[144:147], v[176:179], v[44:47]
	v_mfma_f32_16x16x32_bf16 v[40:43], v[152:155], v[176:179], v[40:43]
	v_mfma_f32_16x16x32_bf16 v[36:39], v[144:147], v[184:187], v[36:39]
	v_mfma_f32_16x16x32_bf16 v[32:35], v[152:155], v[184:187], v[32:35]
	v_mfma_f32_16x16x32_bf16 v[68:71], v[148:151], v[164:167], v[68:71]
	v_mfma_f32_16x16x32_bf16 v[60:63], v[156:159], v[164:167], v[60:63]
	v_mfma_f32_16x16x32_bf16 v[52:55], v[148:151], v[172:175], v[52:55]
	v_mfma_f32_16x16x32_bf16 v[48:51], v[156:159], v[172:175], v[48:51]
	v_mfma_f32_16x16x32_bf16 v[44:47], v[148:151], v[180:183], v[44:47]
	v_mfma_f32_16x16x32_bf16 v[40:43], v[156:159], v[180:183], v[40:43]
	v_mfma_f32_16x16x32_bf16 v[36:39], v[148:151], v[210:213], v[36:39]
	v_mfma_f32_16x16x32_bf16 v[32:35], v[156:159], v[210:213], v[32:35]
	s_setprio 0
; #define PG8_STAGE(bufoff, gbase, voff) do { _Pragma("unroll") for (int _i = 0; _i < 2; ++_i) \
;         __builtin_amdgcn_global_load_lds((const unsigned*)((const char*)(gbase) + (voff)[_i]), (LAS unsigned*)(lds + (bufoff) + ldsw + _i * 8192), 16, 0, 0); } while (0)
; #define PG8_LDA(dst, b, h) do { _Pragma("unroll") for (int m = 0; m < 4; ++m) _Pragma("unroll") for (int k = 0; k < 2; ++k) dst[m][k] = *(const LAS bf16x8*)(lds + PG8_SA(b, h) + aoff + m * 2048 + k * 1024); } while (0)
; #define PG8_MMA(ai, bj, At, Bt) do { __builtin_amdgcn_s_setprio(1); _Pragma("unroll") for (int m = 0; m < 4; ++m) _Pragma("unroll") for (int n = 0; n < 2; ++n) _Pragma("unroll") for (int k = 0; k < 2; ++k) \
;         acc[ai][bj][m][n] = __builtin_amdgcn_mfma_f32_16x16x32_bf16(Bt[n][k], At[m][k], acc[ai][bj][m][n], 0, 0, 0); __builtin_amdgcn_s_setprio(0); } while (0)
; #define PG8_WAIT_V(n) asm volatile("s_waitcnt vmcnt(" #n ")" ::: "memory")
; #define PG8_WAIT_L(n) asm volatile("s_waitcnt lgkmcnt(" #n ")" ::: "memory")
; #define PG8_BAR __builtin_amdgcn_s_barrier()
; #define PG8_SCHED __builtin_amdgcn_sched_barrier(0)
; template <class Epi, class Sched>
; __device__ __forceinline__ void gemm_phase(LAS unsigned char* lds, const GemmP g, const Sched& S, const Epi& E, int tid) {
;     ...
;             PG8_LDA(At, 1, 1); PG8_STAGE(PG8_SB(1, 0), b3, voffB); PG8_STAGE(PG8_SB(1, 1), b3 + hstepB, voffB); PG8_STAGE(PG8_SA(1, 0), a3, voffA);
;             PG8_WAIT_V(8); PG8_WAIT_L(0); PG8_BAR; PG8_MMA(1, 0, At, B0); PG8_MMA(1, 1, At, B1); PG8_BAR; PG8_SCHED;
;         }
;         if (wr == 0) PG8_BAR;
.Lsk_co_3:
	s_barrier
	s_add_i32 s10, s15, s62
	v_lshl_add_u64 v[198:199], v[198:199], 0, s[80:81]
	s_mov_b32 m0, s10
	ds_read_b128 v[160:163], v215 offset:49152
	ds_read_b128 v[164:167], v215 offset:50176
	ds_read_b128 v[168:171], v215 offset:51200
	ds_read_b128 v[172:175], v215 offset:52224
	ds_read_b128 v[176:179], v215 offset:53248
	ds_read_b128 v[180:183], v215 offset:54272
	ds_read_b128 v[184:187], v215 offset:55296
	ds_read_b128 v[210:213], v215 offset:56320
	global_load_lds_dwordx4 v[198:199], off
	s_add_i32 m0, s10, 0x2000
	s_add_u32 s8, s8, 0x40080
	v_lshl_add_u64 v[198:199], v[200:201], 0, s[80:81]
	s_addc_u32 s9, s9, 0
	s_add_i32 s10, s16, s62
	global_load_lds_dwordx4 v[198:199], off
	v_lshl_add_u64 v[198:199], s[8:9], 0, v[190:191]
	s_mov_b32 m0, s10
	s_nop 0
	global_load_lds_dwordx4 v[198:199], off
	v_lshl_add_u64 v[198:199], s[8:9], 0, v[194:195]
	s_add_i32 m0, s10, 0x2000
	s_nop 0
	global_load_lds_dwordx4 v[198:199], off
	v_lshl_add_u64 v[198:199], v[216:217], 0, s[80:81]
	s_mov_b32 m0, s82
	s_nop 0
	global_load_lds_dwordx4 v[198:199], off
	v_lshl_add_u64 v[198:199], v[220:221], 0, s[80:81]
	s_mov_b32 m0, s0
	s_nop 0
	global_load_lds_dwordx4 v[198:199], off
	s_waitcnt vmcnt(8)
	s_waitcnt lgkmcnt(0)
	s_barrier
	s_cmp_lg_u32 s98, 0
	s_cbranch_scc1 .Lsk_co_4
	s_setprio 1
	s_waitcnt lgkmcnt(0)
	v_mfma_f32_16x16x32_bf16 v[92:95], v[124:127], v[160:163], v[92:95]
	v_mfma_f32_16x16x32_bf16 v[88:91], v[136:139], v[160:163], v[88:91]
	v_mfma_f32_16x16x32_bf16 v[84:87], v[124:127], v[168:171], v[84:87]
	v_mfma_f32_16x16x32_bf16 v[80:83], v[136:139], v[168:171], v[80:83]
	v_mfma_f32_16x16x32_bf16 v[76:79], v[124:127], v[176:179], v[76:79]
	v_mfma_f32_16x16x32_bf16 v[72:75], v[136:139], v[176:179], v[72:75]
	v_mfma_f32_16x16x32_bf16 v[64:67], v[124:127], v[184:187], v[64:67]
	v_mfma_f32_16x16x32_bf16 v[56:59], v[136:139], v[184:187], v[56:59]
	v_mfma_f32_16x16x32_bf16 v[92:95], v[132:135], v[164:167], v[92:95]
	v_mfma_f32_16x16x32_bf16 v[88:91], v[140:143], v[164:167], v[88:91]
	v_mfma_f32_16x16x32_bf16 v[84:87], v[132:135], v[172:175], v[84:87]
	v_mfma_f32_16x16x32_bf16 v[80:83], v[140:143], v[172:175], v[80:83]
	v_mfma_f32_16x16x32_bf16 v[76:79], v[132:135], v[180:183], v[76:79]
	v_mfma_f32_16x16x32_bf16 v[72:75], v[140:143], v[180:183], v[72:75]
	v_mfma_f32_16x16x32_bf16 v[64:67], v[132:135], v[210:213], v[64:67]
	v_mfma_f32_16x16x32_bf16 v[56:59], v[140:143], v[210:213], v[56:59]
	s_setprio 0
	s_setprio 1
	v_mfma_f32_16x16x32_bf16 v[28:31], v[144:147], v[160:163], v[28:31]
	v_mfma_f32_16x16x32_bf16 v[24:27], v[152:155], v[160:163], v[24:27]
	v_mfma_f32_16x16x32_bf16 v[20:23], v[144:147], v[168:171], v[20:23]
	v_mfma_f32_16x16x32_bf16 v[16:19], v[152:155], v[168:171], v[16:19]
	v_mfma_f32_16x16x32_bf16 v[12:15], v[144:147], v[176:179], v[12:15]
	v_mfma_f32_16x16x32_bf16 v[8:11], v[152:155], v[176:179], v[8:11]
	v_mfma_f32_16x16x32_bf16 v[4:7], v[144:147], v[184:187], v[4:7]
	v_mfma_f32_16x16x32_bf16 v[0:3], v[152:155], v[184:187], v[0:3]
	v_mfma_f32_16x16x32_bf16 v[28:31], v[148:151], v[164:167], v[28:31]
	v_mfma_f32_16x16x32_bf16 v[24:27], v[156:159], v[164:167], v[24:27]
	v_mfma_f32_16x16x32_bf16 v[20:23], v[148:151], v[172:175], v[20:23]
	v_mfma_f32_16x16x32_bf16 v[16:19], v[156:159], v[172:175], v[16:19]
	v_mfma_f32_16x16x32_bf16 v[12:15], v[148:151], v[180:183], v[12:15]
	v_mfma_f32_16x16x32_bf16 v[8:11], v[156:159], v[180:183], v[8:11]
	v_mfma_f32_16x16x32_bf16 v[4:7], v[148:151], v[210:213], v[4:7]
	v_mfma_f32_16x16x32_bf16 v[0:3], v[156:159], v[210:213], v[0:3]
	s_setprio 0
.Lsk_co_4:
	s_barrier
	s_add_i32 s14, s14, 2
	s_add_u32 s12, s12, 0x100
	s_addc_u32 s13, s13, 0
	s_add_u32 s6, s6, 0x100
	s_addc_u32 s7, s7, 0
	s_cmp_gt_u32 s14, 13
	s_cbranch_scc0 .LBB0_1163
	s_and_b64 vcc, exec, s[78:79]
	s_cbranch_vccz .LBB0_1166
	s_barrier
